# adaLN silu staging loads batched; P3->P3b: chunk-state units remapped onto the workgroup that ran the chunk conv, grid barrier between them replaced by a workgroup barrier (256-WG grid)
# speedup vs baseline: 1.0532x; 1.0185x over previous
; __device__ __forceinline__ float siluf_(float x) { return x * __builtin_amdgcn_rcpf(1.f + fexp(-x)); }
; __device__ __forceinline__ void phase_convert(Ctx& C, int l, LAS unsigned char* lds, const int it_lo, const int it_hi, const int nmod) {
;     ...
;         const float* w_ada = C.in[10] + (size_t)ml * 1024 * 6144; const float* b_ada = C.in[11] + (size_t)ml * 6144;
;         const int col = C.tid & 63, ksl = C.tid >> 6, n = task * 64 + col;
;         for (int pass = 0; pass < 2; ++pass) {
;             for (int i = C.tid; i < 18 * 1024; i += 512) { const int cb = pass * 18 + (i >> 10), k = i & 1023; const float cv = cb < 4 ? C.in[8][cb * 1024 + k] : C.in[9][(cb - 4) * 1024 + k]; sl[i] = siluf_(cv); }
;             __syncthreads();
.LBB0_76:
	s_and_saveexec_b64 s[10:11], s[4:5]
	s_cbranch_execz .LBB0_83
	v_readlane_b32 s40, v253, 18
	v_readlane_b32 s41, v253, 19
	v_readlane_b32 s42, v253, 20
	v_readlane_b32 s43, v253, 21
	v_lshlrev_b32_e32 v42, 2, v176
	v_add_u32_e32 v43, 0x800, v42
	v_add_u32_e32 v45, 0x10000, v129
	s_nop 4
	s_add_u32 s20, s18, 0
	s_cmp_lt_u32 s20, 4
	s_cselect_b32 s72, s40, s42
	s_cselect_b32 s73, s41, s43
	s_cselect_b32 s21, 0, 4
	s_sub_u32 s20, s20, s21
	s_lshl_b32 s20, s20, 12
	s_add_u32 s72, s72, s20
	s_addc_u32 s73, s73, 0
	global_load_dword v6, v42, s[72:73]
	global_load_dword v7, v43, s[72:73]
	s_add_u32 s20, s18, 1
	s_cmp_lt_u32 s20, 4
	s_cselect_b32 s72, s40, s42
	s_cselect_b32 s73, s41, s43
	s_cselect_b32 s21, 0, 4
	s_sub_u32 s20, s20, s21
	s_lshl_b32 s20, s20, 12
	s_add_u32 s72, s72, s20
	s_addc_u32 s73, s73, 0
	global_load_dword v8, v42, s[72:73]
	global_load_dword v9, v43, s[72:73]
	s_add_u32 s20, s18, 2
	s_cmp_lt_u32 s20, 4
	s_cselect_b32 s72, s40, s42
	s_cselect_b32 s73, s41, s43
	s_cselect_b32 s21, 0, 4
	s_sub_u32 s20, s20, s21
	s_lshl_b32 s20, s20, 12
	s_add_u32 s72, s72, s20
	s_addc_u32 s73, s73, 0
	global_load_dword v10, v42, s[72:73]
	global_load_dword v11, v43, s[72:73]
	s_add_u32 s20, s18, 3
	s_cmp_lt_u32 s20, 4
	s_cselect_b32 s72, s40, s42
	s_cselect_b32 s73, s41, s43
	s_cselect_b32 s21, 0, 4
	s_sub_u32 s20, s20, s21
	s_lshl_b32 s20, s20, 12
	s_add_u32 s72, s72, s20
	s_addc_u32 s73, s73, 0
	global_load_dword v12, v42, s[72:73]
	global_load_dword v13, v43, s[72:73]
	s_add_u32 s20, s18, 4
	s_cmp_lt_u32 s20, 4
	s_cselect_b32 s72, s40, s42
	s_cselect_b32 s73, s41, s43
	s_cselect_b32 s21, 0, 4
	s_sub_u32 s20, s20, s21
	s_lshl_b32 s20, s20, 12
	s_add_u32 s72, s72, s20
	s_addc_u32 s73, s73, 0
	global_load_dword v14, v42, s[72:73]
	global_load_dword v15, v43, s[72:73]
	s_add_u32 s20, s18, 5
	s_cmp_lt_u32 s20, 4
	s_cselect_b32 s72, s40, s42
	s_cselect_b32 s73, s41, s43
	s_cselect_b32 s21, 0, 4
	s_sub_u32 s20, s20, s21
	s_lshl_b32 s20, s20, 12
	s_add_u32 s72, s72, s20
	s_addc_u32 s73, s73, 0
	global_load_dword v16, v42, s[72:73]
	global_load_dword v17, v43, s[72:73]
	s_add_u32 s20, s18, 6
	s_cmp_lt_u32 s20, 4
	s_cselect_b32 s72, s40, s42
	s_cselect_b32 s73, s41, s43
	s_cselect_b32 s21, 0, 4
	s_sub_u32 s20, s20, s21
	s_lshl_b32 s20, s20, 12
	s_add_u32 s72, s72, s20
	s_addc_u32 s73, s73, 0
	global_load_dword v18, v42, s[72:73]
	global_load_dword v19, v43, s[72:73]
	s_add_u32 s20, s18, 7
	s_cmp_lt_u32 s20, 4
	s_cselect_b32 s72, s40, s42
	s_cselect_b32 s73, s41, s43
	s_cselect_b32 s21, 0, 4
	s_sub_u32 s20, s20, s21
	s_lshl_b32 s20, s20, 12
	s_add_u32 s72, s72, s20
	s_addc_u32 s73, s73, 0
	global_load_dword v20, v42, s[72:73]
	global_load_dword v21, v43, s[72:73]
	s_add_u32 s20, s18, 8
	s_cmp_lt_u32 s20, 4
	s_cselect_b32 s72, s40, s42
	s_cselect_b32 s73, s41, s43
	s_cselect_b32 s21, 0, 4
	s_sub_u32 s20, s20, s21
	s_lshl_b32 s20, s20, 12
	s_add_u32 s72, s72, s20
	s_addc_u32 s73, s73, 0
	global_load_dword v22, v42, s[72:73]
	global_load_dword v23, v43, s[72:73]
	s_add_u32 s20, s18, 9
	s_cmp_lt_u32 s20, 4
	s_cselect_b32 s72, s40, s42
	s_cselect_b32 s73, s41, s43
	s_cselect_b32 s21, 0, 4
	s_sub_u32 s20, s20, s21
	s_lshl_b32 s20, s20, 12
	s_add_u32 s72, s72, s20
	s_addc_u32 s73, s73, 0
	global_load_dword v24, v42, s[72:73]
	global_load_dword v25, v43, s[72:73]
	s_add_u32 s20, s18, 10
	s_cmp_lt_u32 s20, 4
	s_cselect_b32 s72, s40, s42
	s_cselect_b32 s73, s41, s43
	s_cselect_b32 s21, 0, 4
	s_sub_u32 s20, s20, s21
	s_lshl_b32 s20, s20, 12
	s_add_u32 s72, s72, s20
	s_addc_u32 s73, s73, 0
	global_load_dword v26, v42, s[72:73]
	global_load_dword v27, v43, s[72:73]
	s_add_u32 s20, s18, 11
	s_cmp_lt_u32 s20, 4
	s_cselect_b32 s72, s40, s42
	s_cselect_b32 s73, s41, s43
	s_cselect_b32 s21, 0, 4
	s_sub_u32 s20, s20, s21
	s_lshl_b32 s20, s20, 12
	s_add_u32 s72, s72, s20
	s_addc_u32 s73, s73, 0
	global_load_dword v28, v42, s[72:73]
	global_load_dword v29, v43, s[72:73]
	s_add_u32 s20, s18, 12
	s_cmp_lt_u32 s20, 4
	s_cselect_b32 s72, s40, s42
	s_cselect_b32 s73, s41, s43
	s_cselect_b32 s21, 0, 4
	s_sub_u32 s20, s20, s21
	s_lshl_b32 s20, s20, 12
	s_add_u32 s72, s72, s20
	s_addc_u32 s73, s73, 0
	global_load_dword v30, v42, s[72:73]
	global_load_dword v31, v43, s[72:73]
	s_add_u32 s20, s18, 13
	s_cmp_lt_u32 s20, 4
	s_cselect_b32 s72, s40, s42
	s_cselect_b32 s73, s41, s43
	s_cselect_b32 s21, 0, 4
	s_sub_u32 s20, s20, s21
	s_lshl_b32 s20, s20, 12
	s_add_u32 s72, s72, s20
	s_addc_u32 s73, s73, 0
	global_load_dword v32, v42, s[72:73]
	global_load_dword v33, v43, s[72:73]
	s_add_u32 s20, s18, 14
	s_cmp_lt_u32 s20, 4
	s_cselect_b32 s72, s40, s42
	s_cselect_b32 s73, s41, s43
	s_cselect_b32 s21, 0, 4
	s_sub_u32 s20, s20, s21
	s_lshl_b32 s20, s20, 12
	s_add_u32 s72, s72, s20
	s_addc_u32 s73, s73, 0
	global_load_dword v34, v42, s[72:73]
	global_load_dword v35, v43, s[72:73]
	s_add_u32 s20, s18, 15
	s_cmp_lt_u32 s20, 4
	s_cselect_b32 s72, s40, s42
	s_cselect_b32 s73, s41, s43
	s_cselect_b32 s21, 0, 4
	s_sub_u32 s20, s20, s21
	s_lshl_b32 s20, s20, 12
	s_add_u32 s72, s72, s20
	s_addc_u32 s73, s73, 0
	global_load_dword v36, v42, s[72:73]
	global_load_dword v37, v43, s[72:73]
	s_add_u32 s20, s18, 16
	s_cmp_lt_u32 s20, 4
	s_cselect_b32 s72, s40, s42
	s_cselect_b32 s73, s41, s43
	s_cselect_b32 s21, 0, 4
	s_sub_u32 s20, s20, s21
	s_lshl_b32 s20, s20, 12
	s_add_u32 s72, s72, s20
	s_addc_u32 s73, s73, 0
	global_load_dword v38, v42, s[72:73]
	global_load_dword v39, v43, s[72:73]
	s_add_u32 s20, s18, 17
	s_cmp_lt_u32 s20, 4
	s_cselect_b32 s72, s40, s42
	s_cselect_b32 s73, s41, s43
	s_cselect_b32 s21, 0, 4
	s_sub_u32 s20, s20, s21
	s_lshl_b32 s20, s20, 12
	s_add_u32 s72, s72, s20
	s_addc_u32 s73, s73, 0
	global_load_dword v40, v42, s[72:73]
	global_load_dword v41, v43, s[72:73]
	s_waitcnt vmcnt(0)
; __device__ __forceinline__ float fexp(float x) { return __builtin_amdgcn_exp2f(x * LOG2E); }
; __device__ __forceinline__ float siluf_(float x) { return x * __builtin_amdgcn_rcpf(1.f + fexp(-x)); }
; __device__ __forceinline__ void phase_convert(Ctx& C, int l, LAS unsigned char* lds, const int it_lo, const int it_hi, const int nmod) {
;     ...
;             for (int i = C.tid; i < 18 * 1024; i += 512) { const int cb = pass * 18 + (i >> 10), k = i & 1023; const float cv = cb < 4 ? C.in[8][cb * 1024 + k] : C.in[9][(cb - 4) * 1024 + k]; sl[i] = siluf_(cv); }
;             __syncthreads();
	v_mul_f32_e32 v44, 0xbfb8aa3b, v6
	v_mul_f32_e32 v46, 0xbfb8aa3b, v7
	v_exp_f32_e32 v44, v44
	v_exp_f32_e32 v46, v46
	s_nop 0
	v_add_f32_e32 v44, 1.0, v44
	v_add_f32_e32 v46, 1.0, v46
	v_rcp_f32_e32 v44, v44
	v_rcp_f32_e32 v46, v46
	s_nop 0
	v_mul_f32_e32 v6, v6, v44
	v_mul_f32_e32 v7, v7, v46
	ds_write_b32 v129, v6
	ds_write_b32 v129, v7 offset:2048
	v_mul_f32_e32 v44, 0xbfb8aa3b, v8
	v_mul_f32_e32 v46, 0xbfb8aa3b, v9
	v_exp_f32_e32 v44, v44
	v_exp_f32_e32 v46, v46
	s_nop 0
	v_add_f32_e32 v44, 1.0, v44
	v_add_f32_e32 v46, 1.0, v46
	v_rcp_f32_e32 v44, v44
	v_rcp_f32_e32 v46, v46
	s_nop 0
	v_mul_f32_e32 v8, v8, v44
	v_mul_f32_e32 v9, v9, v46
	ds_write_b32 v129, v8 offset:4096
	ds_write_b32 v129, v9 offset:6144
	v_mul_f32_e32 v44, 0xbfb8aa3b, v10
	v_mul_f32_e32 v46, 0xbfb8aa3b, v11
	v_exp_f32_e32 v44, v44
	v_exp_f32_e32 v46, v46
	s_nop 0
	v_add_f32_e32 v44, 1.0, v44
	v_add_f32_e32 v46, 1.0, v46
	v_rcp_f32_e32 v44, v44
	v_rcp_f32_e32 v46, v46
	s_nop 0
	v_mul_f32_e32 v10, v10, v44
	v_mul_f32_e32 v11, v11, v46
	ds_write_b32 v129, v10 offset:8192
	ds_write_b32 v129, v11 offset:10240
	v_mul_f32_e32 v44, 0xbfb8aa3b, v12
	v_mul_f32_e32 v46, 0xbfb8aa3b, v13
	v_exp_f32_e32 v44, v44
	v_exp_f32_e32 v46, v46
	s_nop 0
	v_add_f32_e32 v44, 1.0, v44
	v_add_f32_e32 v46, 1.0, v46
	v_rcp_f32_e32 v44, v44
	v_rcp_f32_e32 v46, v46
	s_nop 0
	v_mul_f32_e32 v12, v12, v44
	v_mul_f32_e32 v13, v13, v46
	ds_write_b32 v129, v12 offset:12288
	ds_write_b32 v129, v13 offset:14336
	v_mul_f32_e32 v44, 0xbfb8aa3b, v14
	v_mul_f32_e32 v46, 0xbfb8aa3b, v15
	v_exp_f32_e32 v44, v44
	v_exp_f32_e32 v46, v46
	s_nop 0
	v_add_f32_e32 v44, 1.0, v44
	v_add_f32_e32 v46, 1.0, v46
	v_rcp_f32_e32 v44, v44
	v_rcp_f32_e32 v46, v46
	s_nop 0
	v_mul_f32_e32 v14, v14, v44
	v_mul_f32_e32 v15, v15, v46
	ds_write_b32 v129, v14 offset:16384
	ds_write_b32 v129, v15 offset:18432
	v_mul_f32_e32 v44, 0xbfb8aa3b, v16
	v_mul_f32_e32 v46, 0xbfb8aa3b, v17
	v_exp_f32_e32 v44, v44
	v_exp_f32_e32 v46, v46
	s_nop 0
	v_add_f32_e32 v44, 1.0, v44
	v_add_f32_e32 v46, 1.0, v46
	v_rcp_f32_e32 v44, v44
	v_rcp_f32_e32 v46, v46
	s_nop 0
	v_mul_f32_e32 v16, v16, v44
	v_mul_f32_e32 v17, v17, v46
	ds_write_b32 v129, v16 offset:20480
	ds_write_b32 v129, v17 offset:22528
	v_mul_f32_e32 v44, 0xbfb8aa3b, v18
	v_mul_f32_e32 v46, 0xbfb8aa3b, v19
	v_exp_f32_e32 v44, v44
	v_exp_f32_e32 v46, v46
	s_nop 0
	v_add_f32_e32 v44, 1.0, v44
	v_add_f32_e32 v46, 1.0, v46
	v_rcp_f32_e32 v44, v44
	v_rcp_f32_e32 v46, v46
	s_nop 0
	v_mul_f32_e32 v18, v18, v44
	v_mul_f32_e32 v19, v19, v46
	ds_write_b32 v129, v18 offset:24576
	ds_write_b32 v129, v19 offset:26624
	v_mul_f32_e32 v44, 0xbfb8aa3b, v20
	v_mul_f32_e32 v46, 0xbfb8aa3b, v21
	v_exp_f32_e32 v44, v44
	v_exp_f32_e32 v46, v46
	s_nop 0
	v_add_f32_e32 v44, 1.0, v44
	v_add_f32_e32 v46, 1.0, v46
	v_rcp_f32_e32 v44, v44
	v_rcp_f32_e32 v46, v46
	s_nop 0
	v_mul_f32_e32 v20, v20, v44
	v_mul_f32_e32 v21, v21, v46
	ds_write_b32 v129, v20 offset:28672
	ds_write_b32 v129, v21 offset:30720
	v_mul_f32_e32 v44, 0xbfb8aa3b, v22
	v_mul_f32_e32 v46, 0xbfb8aa3b, v23
	v_exp_f32_e32 v44, v44
	v_exp_f32_e32 v46, v46
	s_nop 0
	v_add_f32_e32 v44, 1.0, v44
	v_add_f32_e32 v46, 1.0, v46
	v_rcp_f32_e32 v44, v44
	v_rcp_f32_e32 v46, v46
	s_nop 0
	v_mul_f32_e32 v22, v22, v44
	v_mul_f32_e32 v23, v23, v46
	ds_write_b32 v129, v22 offset:32768
	ds_write_b32 v129, v23 offset:34816
	v_mul_f32_e32 v44, 0xbfb8aa3b, v24
	v_mul_f32_e32 v46, 0xbfb8aa3b, v25
	v_exp_f32_e32 v44, v44
	v_exp_f32_e32 v46, v46
	s_nop 0
	v_add_f32_e32 v44, 1.0, v44
	v_add_f32_e32 v46, 1.0, v46
	v_rcp_f32_e32 v44, v44
	v_rcp_f32_e32 v46, v46
	s_nop 0
	v_mul_f32_e32 v24, v24, v44
	v_mul_f32_e32 v25, v25, v46
	ds_write_b32 v129, v24 offset:36864
	ds_write_b32 v129, v25 offset:38912
	v_mul_f32_e32 v44, 0xbfb8aa3b, v26
	v_mul_f32_e32 v46, 0xbfb8aa3b, v27
	v_exp_f32_e32 v44, v44
	v_exp_f32_e32 v46, v46
	s_nop 0
	v_add_f32_e32 v44, 1.0, v44
	v_add_f32_e32 v46, 1.0, v46
	v_rcp_f32_e32 v44, v44
	v_rcp_f32_e32 v46, v46
	s_nop 0
	v_mul_f32_e32 v26, v26, v44
	v_mul_f32_e32 v27, v27, v46
	ds_write_b32 v129, v26 offset:40960
	ds_write_b32 v129, v27 offset:43008
	v_mul_f32_e32 v44, 0xbfb8aa3b, v28
	v_mul_f32_e32 v46, 0xbfb8aa3b, v29
	v_exp_f32_e32 v44, v44
	v_exp_f32_e32 v46, v46
	s_nop 0
	v_add_f32_e32 v44, 1.0, v44
	v_add_f32_e32 v46, 1.0, v46
	v_rcp_f32_e32 v44, v44
	v_rcp_f32_e32 v46, v46
	s_nop 0
	v_mul_f32_e32 v28, v28, v44
	v_mul_f32_e32 v29, v29, v46
	ds_write_b32 v129, v28 offset:45056
	ds_write_b32 v129, v29 offset:47104
	v_mul_f32_e32 v44, 0xbfb8aa3b, v30
	v_mul_f32_e32 v46, 0xbfb8aa3b, v31
	v_exp_f32_e32 v44, v44
	v_exp_f32_e32 v46, v46
	s_nop 0
	v_add_f32_e32 v44, 1.0, v44
	v_add_f32_e32 v46, 1.0, v46
	v_rcp_f32_e32 v44, v44
	v_rcp_f32_e32 v46, v46
	s_nop 0
	v_mul_f32_e32 v30, v30, v44
	v_mul_f32_e32 v31, v31, v46
	ds_write_b32 v129, v30 offset:49152
	ds_write_b32 v129, v31 offset:51200
	v_mul_f32_e32 v44, 0xbfb8aa3b, v32
	v_mul_f32_e32 v46, 0xbfb8aa3b, v33
	v_exp_f32_e32 v44, v44
	v_exp_f32_e32 v46, v46
	s_nop 0
	v_add_f32_e32 v44, 1.0, v44
	v_add_f32_e32 v46, 1.0, v46
	v_rcp_f32_e32 v44, v44
	v_rcp_f32_e32 v46, v46
	s_nop 0
	v_mul_f32_e32 v32, v32, v44
	v_mul_f32_e32 v33, v33, v46
	ds_write_b32 v129, v32 offset:53248
	ds_write_b32 v129, v33 offset:55296
	v_mul_f32_e32 v44, 0xbfb8aa3b, v34
	v_mul_f32_e32 v46, 0xbfb8aa3b, v35
	v_exp_f32_e32 v44, v44
	v_exp_f32_e32 v46, v46
	s_nop 0
	v_add_f32_e32 v44, 1.0, v44
	v_add_f32_e32 v46, 1.0, v46
	v_rcp_f32_e32 v44, v44
	v_rcp_f32_e32 v46, v46
	s_nop 0
	v_mul_f32_e32 v34, v34, v44
	v_mul_f32_e32 v35, v35, v46
	ds_write_b32 v129, v34 offset:57344
	ds_write_b32 v129, v35 offset:59392
	v_mul_f32_e32 v44, 0xbfb8aa3b, v36
	v_mul_f32_e32 v46, 0xbfb8aa3b, v37
	v_exp_f32_e32 v44, v44
	v_exp_f32_e32 v46, v46
	s_nop 0
	v_add_f32_e32 v44, 1.0, v44
	v_add_f32_e32 v46, 1.0, v46
	v_rcp_f32_e32 v44, v44
	v_rcp_f32_e32 v46, v46
	s_nop 0
	v_mul_f32_e32 v36, v36, v44
	v_mul_f32_e32 v37, v37, v46
	ds_write_b32 v129, v36 offset:61440
	ds_write_b32 v129, v37 offset:63488
	v_mul_f32_e32 v44, 0xbfb8aa3b, v38
	v_mul_f32_e32 v46, 0xbfb8aa3b, v39
	v_exp_f32_e32 v44, v44
	v_exp_f32_e32 v46, v46
	s_nop 0
	v_add_f32_e32 v44, 1.0, v44
	v_add_f32_e32 v46, 1.0, v46
	v_rcp_f32_e32 v44, v44
	v_rcp_f32_e32 v46, v46
	s_nop 0
	v_mul_f32_e32 v38, v38, v44
	v_mul_f32_e32 v39, v39, v46
	ds_write_b32 v45, v38
	ds_write_b32 v45, v39 offset:2048
	v_mul_f32_e32 v44, 0xbfb8aa3b, v40
	v_mul_f32_e32 v46, 0xbfb8aa3b, v41
	v_exp_f32_e32 v44, v44
	v_exp_f32_e32 v46, v46
	s_nop 0
	v_add_f32_e32 v44, 1.0, v44
	v_add_f32_e32 v46, 1.0, v46
	v_rcp_f32_e32 v44, v44
	v_rcp_f32_e32 v46, v46
	s_nop 0
	v_mul_f32_e32 v40, v40, v44
	v_mul_f32_e32 v41, v41, v46
	ds_write_b32 v45, v40 offset:4096
	ds_write_b32 v45, v41 offset:6144

; __device__ __forceinline__ unsigned xb_ld(unsigned* p)              { return __hip_atomic_load(p, __ATOMIC_RELAXED, __HIP_MEMORY_SCOPE_AGENT); }
; __device__ __forceinline__ unsigned xb_add(unsigned* p, unsigned v) { return __hip_atomic_fetch_add(p, v, __ATOMIC_RELAXED, __HIP_MEMORY_SCOPE_AGENT); }
; #define XB_SPIN(cond, bar) do { unsigned _sp = 0; while (cond) { __builtin_amdgcn_s_sleep(1); \
;     if ((++_sp & 255u) == 0u) { if (xb_ld(&(bar)[XB_TMO])) break; if (_sp > XB_SPIN_CAP) { atomicAdd(&(bar)[XB_TMO], 1u); break; } } } } while (0)
; #define PHASE_BEGIN() do { int t_ = C.tid; asm volatile("" : "+v"(t_)); C.tid = t_; C.lane = t_ & 63; C.wave = __builtin_amdgcn_readfirstlane(t_ >> 6); \
;         int g_ = C.G, b_ = C.bid; asm volatile("" : "+s"(g_), "+s"(b_)); C.G = g_; C.bid = b_; } while (0)
; __device__ __forceinline__ void xcd_barrier(const XcdBarrier& b) {
;     asm volatile("s_waitcnt vmcnt(0)" ::: "memory");
;     __syncthreads();
;     if (threadIdx.x == 0) {
;         unsigned* bar = b.bar;
;         __builtin_amdgcn_s_waitcnt(0);
;         unsigned nloc = b.st[0], nx = b.st[1];
;         if (nloc == 0u) { xcd_barrier_complete(bar, b.x, nloc, nx); b.st[0] = nloc; b.st[1] = nx; }
;         const unsigned old = xb_add(&bar[XB_XSUB(b.x)], 1u);
;         const unsigned gen = old / nloc;
;         if (old + 1u == (gen + 1u) * nloc) {
;             __builtin_amdgcn_fence(__ATOMIC_RELEASE, "agent");
;             asm volatile("s_waitcnt vmcnt(0)" ::: "memory");
;             const unsigned og = xb_add(&bar[XB_TOP], 1u);
;             const unsigned tg = og / nx;
;             if (og + 1u == (tg + 1u) * nx) xb_add(&bar[XB_TOPGEN], 1u);
;             else XB_SPIN(xb_ld(&bar[XB_TOPGEN]) == tg, bar);
;             __builtin_amdgcn_fence(__ATOMIC_ACQUIRE, "agent");
;             xb_add(&bar[XB_XGEN(b.x)], 1u);
;             asm volatile("s_waitcnt vmcnt(0)" ::: "memory");
;         } else {
;             XB_SPIN(xb_ld(&bar[XB_XGEN(b.x)]) == gen, bar);
;             __builtin_amdgcn_fence(__ATOMIC_ACQUIRE, "agent");
;             asm volatile("s_waitcnt vmcnt(0)" ::: "memory");
;         }
;     }
;     __syncthreads();
; }
; __global__ void __launch_bounds__(512) fwd_megakernel(Args args) {
;     ...
;         GSYNC(); PHASE_BEGIN();
.LBB0_565:
	s_or_b64 exec, exec, s[4:5]
	s_cmp_eq_u32 s26, 0x100
	s_cbranch_scc0 .Lgs_p3_keep
	s_waitcnt vmcnt(0) lgkmcnt(0)
	s_barrier
	s_branch .Lgs_p3_bypass
.Lgs_p3_keep:
	s_getreg_b32 s4, hwreg(HW_REG_XCC_ID, 0, 4)
	s_waitcnt vmcnt(0)
	s_barrier
	s_mov_b64 s[2:3], exec
	v_readlane_b32 s6, v253, 52
	v_readlane_b32 s7, v253, 53
	s_and_b64 s[6:7], s[2:3], s[6:7]
	s_xor_b64 s[2:3], s[6:7], s[2:3]
	s_mov_b64 exec, s[6:7]
	s_cbranch_execz .LBB0_618
	v_readlane_b32 s5, v255, 36
	s_waitcnt vmcnt(0) expcnt(0) lgkmcnt(0)
	s_and_b32 s10, s4, 15
	v_mov_b32_e32 v0, s5
	ds_read_b32 v2, v0
	v_readlane_b32 s5, v255, 37
	s_waitcnt lgkmcnt(0)
	v_cmp_ne_u32_e32 vcc, 0, v2
	v_mov_b32_e32 v0, s5
	ds_read_b32 v0, v0
	s_cbranch_vccnz .LBB0_581
	s_mov_b32 s11, 1
	s_branch .LBB0_569

; #define PHASE_BEGIN() do { int t_ = C.tid; asm volatile("" : "+v"(t_)); C.tid = t_; C.lane = t_ & 63; C.wave = __builtin_amdgcn_readfirstlane(t_ >> 6); \
;         int g_ = C.G, b_ = C.bid; asm volatile("" : "+s"(g_), "+s"(b_)); C.G = g_; C.bid = b_; } while (0)
; __global__ void __launch_bounds__(512) fwd_megakernel(Args args) {
;     ...
;             for (int u = C.bid; u < NM_S + NM_P; u += C.G) {
;                 PHASE_BEGIN();
;                 if (u < NM_S) mstate_task<true>(C, l, u >> 1, 2 * (u & 1) + (C.wave >> 2), C.wave & 3, wb);
;                 else { const int v = u - NM_S; mstate_task<false>(C, l, v >> 1, 2 * (v & 1) + (C.wave >> 2), C.wave & 3, wb); }
;             }
.Lgs_p3_bypass:
	s_cmpk_gt_i32 s72, 0x43f
	v_readfirstlane_b32 s2, v202
	s_cbranch_scc1 .LBB0_637
	s_lshl_b32 s2, s2, 2
	s_and_b32 s2, s2, 0xffffff00
	s_add_i32 s22, s2, 0
	s_mov_b32 s76, s72
	s_cmp_eq_u32 s26, 0x100
	s_cbranch_scc0 .Lms_init_done
	s_lshl_b32 s72, s72, 1
	s_addk_i32 s72, 64
.Lms_init_done:
	s_branch .LBB0_622
.LBB0_620:
	s_or_b64 exec, exec, s[4:5]
	s_waitcnt lgkmcnt(0)
.LBB0_621:
	s_cmp_eq_u32 s26, 0x100
	s_cbranch_scc0 .Lms_generic
	s_bitcmp1_b32 s72, 0
	s_cbranch_scc1 .Lms_pair_done
	s_add_i32 s72, s72, 1
	s_branch .LBB0_622
.Lms_pair_done:
	s_sub_u32 s2, s72, 1
	s_cmp_lt_u32 s2, 64
	s_cbranch_scc1 .Lms_sample_done
	s_cmp_lt_u32 s2, 0x240
	s_cbranch_scc0 .Lms_second_done
	s_add_i32 s72, s2, 0x200
	s_branch .LBB0_622
.Lms_second_done:
	s_sub_u32 s2, s2, 0x240
	s_lshr_b32 s2, s2, 1
	s_bitcmp1_b32 s2, 0
	s_cbranch_scc1 .LBB0_638
	s_cmp_lt_u32 s2, 48
	s_cbranch_scc0 .LBB0_638
	s_mov_b32 s72, s2
	s_branch .LBB0_622
.Lms_sample_done:
	s_cmp_lt_u32 s2, 16
	s_cbranch_scc0 .LBB0_638
	s_add_i32 s72, s2, 48
	s_branch .LBB0_622
